# FoX first-tile search done in one parallel probe; FoX Q prologue loads batched; PROJ epilogue row-rstd loaded once per tile
# speedup vs baseline: 1.0540x; 1.0119x over previous
.Lgm0_loop:
	v_add_u32_e32 v248, s30, v155
	v_add_u32_e32 v249, s30, v160
	v_mfma_f32_16x16x32_bf16 v[128:131], v[212:215], v[186:189], v[128:131]
	ds_read_b128 v[0:3], v248
	v_mfma_f32_16x16x32_bf16 v[96:99], v[212:215], v[190:193], v[96:99]
	ds_read_b128 v[16:19], v249 offset:8192
	v_mfma_f32_16x16x32_bf16 v[108:111], v[212:215], v[194:197], v[108:111]
	ds_read_b128 v[4:7], v248 offset:1024
	v_mfma_f32_16x16x32_bf16 v[132:135], v[212:215], v[208:211], v[132:135]
	ds_read_b128 v[20:23], v249 offset:9216
	v_mfma_f32_16x16x32_bf16 v[116:119], v[216:219], v[186:189], v[116:119]
	ds_read_b128 v[8:11], v248 offset:2048
	v_mfma_f32_16x16x32_bf16 v[92:95], v[216:219], v[190:193], v[92:95]
	ds_read_b128 v[162:165], v249 offset:10240
	v_mfma_f32_16x16x32_bf16 v[112:115], v[216:219], v[194:197], v[112:115]
	ds_read_b128 v[12:15], v248 offset:3072
	v_mfma_f32_16x16x32_bf16 v[136:139], v[216:219], v[208:211], v[136:139]
	ds_read_b128 v[166:169], v249 offset:11264
	v_mfma_f32_16x16x32_bf16 v[104:107], v[220:223], v[186:189], v[104:107]
	ds_read_b128 v[170:173], v249 offset:12288
	v_mfma_f32_16x16x32_bf16 v[88:91], v[220:223], v[190:193], v[88:91]
	ds_read_b128 v[174:177], v249 offset:13312
	v_mfma_f32_16x16x32_bf16 v[120:123], v[220:223], v[194:197], v[120:123]
	ds_read_b128 v[178:181], v249 offset:14336
	v_mfma_f32_16x16x32_bf16 v[140:143], v[220:223], v[208:211], v[140:143]
	ds_read_b128 v[182:185], v249 offset:15360
	s_add_u32 m0, s25, s24
	v_mfma_f32_16x16x32_bf16 v[100:103], v[224:227], v[186:189], v[100:103]
	global_load_lds_dwordx4 v244, s[26:27]
	v_mfma_f32_16x16x32_bf16 v[84:87], v[224:227], v[190:193], v[84:87]
	v_mfma_f32_16x16x32_bf16 v[124:127], v[224:227], v[194:197], v[124:127]
	s_add_u32 m0, m0, 0x1000
	v_mfma_f32_16x16x32_bf16 v[144:147], v[224:227], v[208:211], v[144:147]
	global_load_lds_dwordx4 v245, s[26:27]
	v_mfma_f32_16x16x32_bf16 v[52:55], v[228:231], v[186:189], v[52:55]
	v_mfma_f32_16x16x32_bf16 v[36:39], v[228:231], v[190:193], v[36:39]
	s_add_u32 m0, m0, 0x1000
	v_mfma_f32_16x16x32_bf16 v[64:67], v[228:231], v[194:197], v[64:67]
	global_load_lds_dwordx4 v244, s[28:29]
	v_mfma_f32_16x16x32_bf16 v[76:79], v[228:231], v[208:211], v[76:79]
	v_mfma_f32_16x16x32_bf16 v[48:51], v[232:235], v[186:189], v[48:51]
	s_add_u32 m0, m0, 0x1000
	v_mfma_f32_16x16x32_bf16 v[32:35], v[232:235], v[190:193], v[32:35]
	global_load_lds_dwordx4 v245, s[28:29]
	v_mfma_f32_16x16x32_bf16 v[68:71], v[232:235], v[194:197], v[68:71]
	v_mfma_f32_16x16x32_bf16 v[72:75], v[232:235], v[208:211], v[72:75]
	s_add_u32 m0, m0, 0x1000
	v_mfma_f32_16x16x32_bf16 v[44:47], v[236:239], v[186:189], v[44:47]
	global_load_lds_dwordx4 v246, s[28:29]
	v_mfma_f32_16x16x32_bf16 v[28:31], v[236:239], v[190:193], v[28:31]
	v_mfma_f32_16x16x32_bf16 v[80:83], v[236:239], v[194:197], v[80:83]
	s_add_u32 m0, m0, 0x1000
	v_mfma_f32_16x16x32_bf16 v[60:63], v[236:239], v[208:211], v[60:63]
	global_load_lds_dwordx4 v247, s[28:29]
	v_mfma_f32_16x16x32_bf16 v[40:43], v[240:243], v[186:189], v[40:43]
	v_mfma_f32_16x16x32_bf16 v[24:27], v[240:243], v[190:193], v[24:27]
	v_mfma_f32_16x16x32_bf16 v[56:59], v[240:243], v[194:197], v[56:59]
	v_mfma_f32_16x16x32_bf16 v[148:151], v[240:243], v[208:211], v[148:151]
	s_add_u32 s26, s26, 64
	s_addc_u32 s27, s27, 0
	s_add_u32 s28, s28, 64
	s_addc_u32 s29, s29, 0
	s_add_u32 s25, s25, 24576
	s_cmp_eq_u32 s25, 73728
	s_cselect_b32 s25, 0, s25
	s_add_u32 s30, s30, 24576
	s_cmp_eq_u32 s30, 73728
	s_cselect_b32 s30, 0, s30
	s_waitcnt vmcnt(6)
	s_waitcnt lgkmcnt(0)
	s_barrier
	v_add_u32_e32 v248, s30, v155
	v_add_u32_e32 v249, s30, v160
	v_mfma_f32_16x16x32_bf16 v[128:131], v[16:19], v[0:3], v[128:131]
	ds_read_b128 v[186:189], v248
	v_mfma_f32_16x16x32_bf16 v[96:99], v[16:19], v[4:7], v[96:99]
	ds_read_b128 v[212:215], v249 offset:8192
	v_mfma_f32_16x16x32_bf16 v[108:111], v[16:19], v[8:11], v[108:111]
	ds_read_b128 v[190:193], v248 offset:1024
	v_mfma_f32_16x16x32_bf16 v[132:135], v[16:19], v[12:15], v[132:135]
	ds_read_b128 v[216:219], v249 offset:9216
	v_mfma_f32_16x16x32_bf16 v[116:119], v[20:23], v[0:3], v[116:119]
	ds_read_b128 v[194:197], v248 offset:2048
	v_mfma_f32_16x16x32_bf16 v[92:95], v[20:23], v[4:7], v[92:95]
	ds_read_b128 v[220:223], v249 offset:10240
	v_mfma_f32_16x16x32_bf16 v[112:115], v[20:23], v[8:11], v[112:115]
	ds_read_b128 v[208:211], v248 offset:3072
	v_mfma_f32_16x16x32_bf16 v[136:139], v[20:23], v[12:15], v[136:139]
	ds_read_b128 v[224:227], v249 offset:11264
	v_mfma_f32_16x16x32_bf16 v[104:107], v[162:165], v[0:3], v[104:107]
	ds_read_b128 v[228:231], v249 offset:12288
	v_mfma_f32_16x16x32_bf16 v[88:91], v[162:165], v[4:7], v[88:91]
	ds_read_b128 v[232:235], v249 offset:13312
	v_mfma_f32_16x16x32_bf16 v[120:123], v[162:165], v[8:11], v[120:123]
	ds_read_b128 v[236:239], v249 offset:14336
	v_mfma_f32_16x16x32_bf16 v[140:143], v[162:165], v[12:15], v[140:143]
	ds_read_b128 v[240:243], v249 offset:15360
	s_add_u32 m0, s25, s24
	v_mfma_f32_16x16x32_bf16 v[100:103], v[166:169], v[0:3], v[100:103]
	global_load_lds_dwordx4 v244, s[26:27]
	v_mfma_f32_16x16x32_bf16 v[84:87], v[166:169], v[4:7], v[84:87]
	v_mfma_f32_16x16x32_bf16 v[124:127], v[166:169], v[8:11], v[124:127]
	s_add_u32 m0, m0, 0x1000
	v_mfma_f32_16x16x32_bf16 v[144:147], v[166:169], v[12:15], v[144:147]
	global_load_lds_dwordx4 v245, s[26:27]
	v_mfma_f32_16x16x32_bf16 v[52:55], v[170:173], v[0:3], v[52:55]
	v_mfma_f32_16x16x32_bf16 v[36:39], v[170:173], v[4:7], v[36:39]
	s_add_u32 m0, m0, 0x1000
	v_mfma_f32_16x16x32_bf16 v[64:67], v[170:173], v[8:11], v[64:67]
	global_load_lds_dwordx4 v244, s[28:29]
	v_mfma_f32_16x16x32_bf16 v[76:79], v[170:173], v[12:15], v[76:79]
	v_mfma_f32_16x16x32_bf16 v[48:51], v[174:177], v[0:3], v[48:51]
	s_add_u32 m0, m0, 0x1000
	v_mfma_f32_16x16x32_bf16 v[32:35], v[174:177], v[4:7], v[32:35]
	global_load_lds_dwordx4 v245, s[28:29]
	v_mfma_f32_16x16x32_bf16 v[68:71], v[174:177], v[8:11], v[68:71]
	v_mfma_f32_16x16x32_bf16 v[72:75], v[174:177], v[12:15], v[72:75]
	s_add_u32 m0, m0, 0x1000
	v_mfma_f32_16x16x32_bf16 v[44:47], v[178:181], v[0:3], v[44:47]
	global_load_lds_dwordx4 v246, s[28:29]
	v_mfma_f32_16x16x32_bf16 v[28:31], v[178:181], v[4:7], v[28:31]
	v_mfma_f32_16x16x32_bf16 v[80:83], v[178:181], v[8:11], v[80:83]
	s_add_u32 m0, m0, 0x1000
	v_mfma_f32_16x16x32_bf16 v[60:63], v[178:181], v[12:15], v[60:63]
	global_load_lds_dwordx4 v247, s[28:29]
	v_mfma_f32_16x16x32_bf16 v[40:43], v[182:185], v[0:3], v[40:43]
	v_mfma_f32_16x16x32_bf16 v[24:27], v[182:185], v[4:7], v[24:27]
	v_mfma_f32_16x16x32_bf16 v[56:59], v[182:185], v[8:11], v[56:59]
	v_mfma_f32_16x16x32_bf16 v[148:151], v[182:185], v[12:15], v[148:151]
	s_add_u32 s26, s26, 64
	s_addc_u32 s27, s27, 0
	s_add_u32 s28, s28, 64
	s_addc_u32 s29, s29, 0
	s_add_u32 s25, s25, 24576
	s_cmp_eq_u32 s25, 73728
	s_cselect_b32 s25, 0, s25
	s_add_u32 s30, s30, 24576
	s_cmp_eq_u32 s30, 73728
	s_cselect_b32 s30, 0, s30
	s_waitcnt vmcnt(6)
	s_waitcnt lgkmcnt(0)
	s_barrier
	s_sub_u32 s31, s31, 1
	s_cmp_lg_u32 s31, 0
	s_cbranch_scc1 .Lgm0_loop
	v_add_u32_e32 v248, s30, v155
	v_add_u32_e32 v249, s30, v160
	v_mfma_f32_16x16x32_bf16 v[128:131], v[212:215], v[186:189], v[128:131]
	ds_read_b128 v[0:3], v248
	v_mfma_f32_16x16x32_bf16 v[96:99], v[212:215], v[190:193], v[96:99]
	ds_read_b128 v[16:19], v249 offset:8192
	v_mfma_f32_16x16x32_bf16 v[108:111], v[212:215], v[194:197], v[108:111]
	ds_read_b128 v[4:7], v248 offset:1024
	v_mfma_f32_16x16x32_bf16 v[132:135], v[212:215], v[208:211], v[132:135]
	ds_read_b128 v[20:23], v249 offset:9216
	v_mfma_f32_16x16x32_bf16 v[116:119], v[216:219], v[186:189], v[116:119]
	ds_read_b128 v[8:11], v248 offset:2048
	v_mfma_f32_16x16x32_bf16 v[92:95], v[216:219], v[190:193], v[92:95]
	ds_read_b128 v[162:165], v249 offset:10240
	v_mfma_f32_16x16x32_bf16 v[112:115], v[216:219], v[194:197], v[112:115]
	ds_read_b128 v[12:15], v248 offset:3072
	v_mfma_f32_16x16x32_bf16 v[136:139], v[216:219], v[208:211], v[136:139]
	ds_read_b128 v[166:169], v249 offset:11264
	v_mfma_f32_16x16x32_bf16 v[104:107], v[220:223], v[186:189], v[104:107]
	ds_read_b128 v[170:173], v249 offset:12288
	v_mfma_f32_16x16x32_bf16 v[88:91], v[220:223], v[190:193], v[88:91]
	ds_read_b128 v[174:177], v249 offset:13312
	v_mfma_f32_16x16x32_bf16 v[120:123], v[220:223], v[194:197], v[120:123]
	ds_read_b128 v[178:181], v249 offset:14336
	v_mfma_f32_16x16x32_bf16 v[140:143], v[220:223], v[208:211], v[140:143]
	ds_read_b128 v[182:185], v249 offset:15360
	s_add_u32 m0, s25, s24
	v_mfma_f32_16x16x32_bf16 v[100:103], v[224:227], v[186:189], v[100:103]
	global_load_lds_dwordx4 v244, s[26:27]
	v_mfma_f32_16x16x32_bf16 v[84:87], v[224:227], v[190:193], v[84:87]
	v_mfma_f32_16x16x32_bf16 v[124:127], v[224:227], v[194:197], v[124:127]
	s_add_u32 m0, m0, 0x1000
	v_mfma_f32_16x16x32_bf16 v[144:147], v[224:227], v[208:211], v[144:147]
	global_load_lds_dwordx4 v245, s[26:27]
	v_mfma_f32_16x16x32_bf16 v[52:55], v[228:231], v[186:189], v[52:55]
	v_mfma_f32_16x16x32_bf16 v[36:39], v[228:231], v[190:193], v[36:39]
	s_add_u32 m0, m0, 0x1000
	v_mfma_f32_16x16x32_bf16 v[64:67], v[228:231], v[194:197], v[64:67]
	global_load_lds_dwordx4 v244, s[28:29]
	v_mfma_f32_16x16x32_bf16 v[76:79], v[228:231], v[208:211], v[76:79]
	v_mfma_f32_16x16x32_bf16 v[48:51], v[232:235], v[186:189], v[48:51]
	s_add_u32 m0, m0, 0x1000
	v_mfma_f32_16x16x32_bf16 v[32:35], v[232:235], v[190:193], v[32:35]
	global_load_lds_dwordx4 v245, s[28:29]
	v_mfma_f32_16x16x32_bf16 v[68:71], v[232:235], v[194:197], v[68:71]
	v_mfma_f32_16x16x32_bf16 v[72:75], v[232:235], v[208:211], v[72:75]
	s_add_u32 m0, m0, 0x1000
	v_mfma_f32_16x16x32_bf16 v[44:47], v[236:239], v[186:189], v[44:47]
	global_load_lds_dwordx4 v246, s[28:29]
	v_mfma_f32_16x16x32_bf16 v[28:31], v[236:239], v[190:193], v[28:31]
	v_mfma_f32_16x16x32_bf16 v[80:83], v[236:239], v[194:197], v[80:83]
	s_add_u32 m0, m0, 0x1000
	v_mfma_f32_16x16x32_bf16 v[60:63], v[236:239], v[208:211], v[60:63]
	global_load_lds_dwordx4 v247, s[28:29]
	v_mfma_f32_16x16x32_bf16 v[40:43], v[240:243], v[186:189], v[40:43]
	v_mfma_f32_16x16x32_bf16 v[24:27], v[240:243], v[190:193], v[24:27]
	v_mfma_f32_16x16x32_bf16 v[56:59], v[240:243], v[194:197], v[56:59]
	v_mfma_f32_16x16x32_bf16 v[148:151], v[240:243], v[208:211], v[148:151]
	s_add_u32 s26, s26, 64
	s_addc_u32 s27, s27, 0
	s_add_u32 s28, s28, 64
	s_addc_u32 s29, s29, 0
	s_add_u32 s25, s25, 24576
	s_cmp_eq_u32 s25, 73728
	s_cselect_b32 s25, 0, s25
	s_add_u32 s30, s30, 24576
	s_cmp_eq_u32 s30, 73728
	s_cselect_b32 s30, 0, s30
	s_waitcnt vmcnt(6)
	s_waitcnt lgkmcnt(0)
	s_barrier
	v_add_u32_e32 v248, s30, v155
	v_add_u32_e32 v249, s30, v160
	v_mfma_f32_16x16x32_bf16 v[128:131], v[16:19], v[0:3], v[128:131]
	ds_read_b128 v[186:189], v248
	v_mfma_f32_16x16x32_bf16 v[96:99], v[16:19], v[4:7], v[96:99]
	ds_read_b128 v[212:215], v249 offset:8192
	v_mfma_f32_16x16x32_bf16 v[108:111], v[16:19], v[8:11], v[108:111]
	ds_read_b128 v[190:193], v248 offset:1024
	v_mfma_f32_16x16x32_bf16 v[132:135], v[16:19], v[12:15], v[132:135]
	ds_read_b128 v[216:219], v249 offset:9216
	v_mfma_f32_16x16x32_bf16 v[116:119], v[20:23], v[0:3], v[116:119]
	ds_read_b128 v[194:197], v248 offset:2048
	v_mfma_f32_16x16x32_bf16 v[92:95], v[20:23], v[4:7], v[92:95]
	ds_read_b128 v[220:223], v249 offset:10240
	v_mfma_f32_16x16x32_bf16 v[112:115], v[20:23], v[8:11], v[112:115]
	ds_read_b128 v[208:211], v248 offset:3072
	v_mfma_f32_16x16x32_bf16 v[136:139], v[20:23], v[12:15], v[136:139]
	ds_read_b128 v[224:227], v249 offset:11264
	v_mfma_f32_16x16x32_bf16 v[104:107], v[162:165], v[0:3], v[104:107]
	ds_read_b128 v[228:231], v249 offset:12288
	v_mfma_f32_16x16x32_bf16 v[88:91], v[162:165], v[4:7], v[88:91]
	ds_read_b128 v[232:235], v249 offset:13312
	v_mfma_f32_16x16x32_bf16 v[120:123], v[162:165], v[8:11], v[120:123]
	ds_read_b128 v[236:239], v249 offset:14336
	v_mfma_f32_16x16x32_bf16 v[140:143], v[162:165], v[12:15], v[140:143]
	ds_read_b128 v[240:243], v249 offset:15360
	v_mfma_f32_16x16x32_bf16 v[100:103], v[166:169], v[0:3], v[100:103]
	v_mfma_f32_16x16x32_bf16 v[84:87], v[166:169], v[4:7], v[84:87]
	v_mfma_f32_16x16x32_bf16 v[124:127], v[166:169], v[8:11], v[124:127]
	v_mfma_f32_16x16x32_bf16 v[144:147], v[166:169], v[12:15], v[144:147]
	v_mfma_f32_16x16x32_bf16 v[52:55], v[170:173], v[0:3], v[52:55]
	v_mfma_f32_16x16x32_bf16 v[36:39], v[170:173], v[4:7], v[36:39]
	v_mfma_f32_16x16x32_bf16 v[64:67], v[170:173], v[8:11], v[64:67]
	v_mfma_f32_16x16x32_bf16 v[76:79], v[170:173], v[12:15], v[76:79]
	v_mfma_f32_16x16x32_bf16 v[48:51], v[174:177], v[0:3], v[48:51]
	v_mfma_f32_16x16x32_bf16 v[32:35], v[174:177], v[4:7], v[32:35]
	v_mfma_f32_16x16x32_bf16 v[68:71], v[174:177], v[8:11], v[68:71]
	v_mfma_f32_16x16x32_bf16 v[72:75], v[174:177], v[12:15], v[72:75]
	v_mfma_f32_16x16x32_bf16 v[44:47], v[178:181], v[0:3], v[44:47]
	v_mfma_f32_16x16x32_bf16 v[28:31], v[178:181], v[4:7], v[28:31]
	v_mfma_f32_16x16x32_bf16 v[80:83], v[178:181], v[8:11], v[80:83]
	v_mfma_f32_16x16x32_bf16 v[60:63], v[178:181], v[12:15], v[60:63]
	v_mfma_f32_16x16x32_bf16 v[40:43], v[182:185], v[0:3], v[40:43]
	v_mfma_f32_16x16x32_bf16 v[24:27], v[182:185], v[4:7], v[24:27]
	v_mfma_f32_16x16x32_bf16 v[56:59], v[182:185], v[8:11], v[56:59]
	v_mfma_f32_16x16x32_bf16 v[148:151], v[182:185], v[12:15], v[148:151]
	s_add_u32 s30, s30, 24576
	s_cmp_eq_u32 s30, 73728
	s_cselect_b32 s30, 0, s30
	s_waitcnt vmcnt(0)
	s_waitcnt lgkmcnt(0)
	s_barrier
	v_add_u32_e32 v248, s30, v155
	v_add_u32_e32 v249, s30, v160
	v_mfma_f32_16x16x32_bf16 v[128:131], v[212:215], v[186:189], v[128:131]
	ds_read_b128 v[0:3], v248
	v_mfma_f32_16x16x32_bf16 v[96:99], v[212:215], v[190:193], v[96:99]
	ds_read_b128 v[16:19], v249 offset:8192
	v_mfma_f32_16x16x32_bf16 v[108:111], v[212:215], v[194:197], v[108:111]
	ds_read_b128 v[4:7], v248 offset:1024
	v_mfma_f32_16x16x32_bf16 v[132:135], v[212:215], v[208:211], v[132:135]
	ds_read_b128 v[20:23], v249 offset:9216
	v_mfma_f32_16x16x32_bf16 v[116:119], v[216:219], v[186:189], v[116:119]
	ds_read_b128 v[8:11], v248 offset:2048
	v_mfma_f32_16x16x32_bf16 v[92:95], v[216:219], v[190:193], v[92:95]
	ds_read_b128 v[162:165], v249 offset:10240
	v_mfma_f32_16x16x32_bf16 v[112:115], v[216:219], v[194:197], v[112:115]
	ds_read_b128 v[12:15], v248 offset:3072
	v_mfma_f32_16x16x32_bf16 v[136:139], v[216:219], v[208:211], v[136:139]
	ds_read_b128 v[166:169], v249 offset:11264
	v_mfma_f32_16x16x32_bf16 v[104:107], v[220:223], v[186:189], v[104:107]
	ds_read_b128 v[170:173], v249 offset:12288
	v_mfma_f32_16x16x32_bf16 v[88:91], v[220:223], v[190:193], v[88:91]
	ds_read_b128 v[174:177], v249 offset:13312
	v_mfma_f32_16x16x32_bf16 v[120:123], v[220:223], v[194:197], v[120:123]
	ds_read_b128 v[178:181], v249 offset:14336
	v_mfma_f32_16x16x32_bf16 v[140:143], v[220:223], v[208:211], v[140:143]
	ds_read_b128 v[182:185], v249 offset:15360
	v_mfma_f32_16x16x32_bf16 v[100:103], v[224:227], v[186:189], v[100:103]
	v_mfma_f32_16x16x32_bf16 v[84:87], v[224:227], v[190:193], v[84:87]
	v_mfma_f32_16x16x32_bf16 v[124:127], v[224:227], v[194:197], v[124:127]
	v_mfma_f32_16x16x32_bf16 v[144:147], v[224:227], v[208:211], v[144:147]
	v_mfma_f32_16x16x32_bf16 v[52:55], v[228:231], v[186:189], v[52:55]
	v_mfma_f32_16x16x32_bf16 v[36:39], v[228:231], v[190:193], v[36:39]
	v_mfma_f32_16x16x32_bf16 v[64:67], v[228:231], v[194:197], v[64:67]
	v_mfma_f32_16x16x32_bf16 v[76:79], v[228:231], v[208:211], v[76:79]
	v_mfma_f32_16x16x32_bf16 v[48:51], v[232:235], v[186:189], v[48:51]
	v_mfma_f32_16x16x32_bf16 v[32:35], v[232:235], v[190:193], v[32:35]
	v_mfma_f32_16x16x32_bf16 v[68:71], v[232:235], v[194:197], v[68:71]
	v_mfma_f32_16x16x32_bf16 v[72:75], v[232:235], v[208:211], v[72:75]
	v_mfma_f32_16x16x32_bf16 v[44:47], v[236:239], v[186:189], v[44:47]
	v_mfma_f32_16x16x32_bf16 v[28:31], v[236:239], v[190:193], v[28:31]
	v_mfma_f32_16x16x32_bf16 v[80:83], v[236:239], v[194:197], v[80:83]
	v_mfma_f32_16x16x32_bf16 v[60:63], v[236:239], v[208:211], v[60:63]
	v_mfma_f32_16x16x32_bf16 v[40:43], v[240:243], v[186:189], v[40:43]
	v_mfma_f32_16x16x32_bf16 v[24:27], v[240:243], v[190:193], v[24:27]
	v_mfma_f32_16x16x32_bf16 v[56:59], v[240:243], v[194:197], v[56:59]
	v_mfma_f32_16x16x32_bf16 v[148:151], v[240:243], v[208:211], v[148:151]
	s_add_u32 s30, s30, 24576
	s_cmp_eq_u32 s30, 73728
	s_cselect_b32 s30, 0, s30
	s_waitcnt lgkmcnt(0)
	s_barrier
	v_mfma_f32_16x16x32_bf16 v[128:131], v[16:19], v[0:3], v[128:131]
	v_mfma_f32_16x16x32_bf16 v[96:99], v[16:19], v[4:7], v[96:99]
	v_mfma_f32_16x16x32_bf16 v[108:111], v[16:19], v[8:11], v[108:111]
	v_mfma_f32_16x16x32_bf16 v[132:135], v[16:19], v[12:15], v[132:135]
	v_mfma_f32_16x16x32_bf16 v[116:119], v[20:23], v[0:3], v[116:119]
	v_mfma_f32_16x16x32_bf16 v[92:95], v[20:23], v[4:7], v[92:95]
	v_mfma_f32_16x16x32_bf16 v[112:115], v[20:23], v[8:11], v[112:115]
	v_mfma_f32_16x16x32_bf16 v[136:139], v[20:23], v[12:15], v[136:139]
	v_mfma_f32_16x16x32_bf16 v[104:107], v[162:165], v[0:3], v[104:107]
	v_mfma_f32_16x16x32_bf16 v[88:91], v[162:165], v[4:7], v[88:91]
	v_mfma_f32_16x16x32_bf16 v[120:123], v[162:165], v[8:11], v[120:123]
	v_mfma_f32_16x16x32_bf16 v[140:143], v[162:165], v[12:15], v[140:143]
	v_mfma_f32_16x16x32_bf16 v[100:103], v[166:169], v[0:3], v[100:103]
	v_mfma_f32_16x16x32_bf16 v[84:87], v[166:169], v[4:7], v[84:87]
	v_mfma_f32_16x16x32_bf16 v[124:127], v[166:169], v[8:11], v[124:127]
	v_mfma_f32_16x16x32_bf16 v[144:147], v[166:169], v[12:15], v[144:147]
	v_mfma_f32_16x16x32_bf16 v[52:55], v[170:173], v[0:3], v[52:55]
	v_mfma_f32_16x16x32_bf16 v[36:39], v[170:173], v[4:7], v[36:39]
	v_mfma_f32_16x16x32_bf16 v[64:67], v[170:173], v[8:11], v[64:67]
	v_mfma_f32_16x16x32_bf16 v[76:79], v[170:173], v[12:15], v[76:79]
	v_mfma_f32_16x16x32_bf16 v[48:51], v[174:177], v[0:3], v[48:51]
	v_mfma_f32_16x16x32_bf16 v[32:35], v[174:177], v[4:7], v[32:35]
	v_mfma_f32_16x16x32_bf16 v[68:71], v[174:177], v[8:11], v[68:71]
	v_mfma_f32_16x16x32_bf16 v[72:75], v[174:177], v[12:15], v[72:75]
	v_mfma_f32_16x16x32_bf16 v[44:47], v[178:181], v[0:3], v[44:47]
	v_mfma_f32_16x16x32_bf16 v[28:31], v[178:181], v[4:7], v[28:31]
	v_mfma_f32_16x16x32_bf16 v[80:83], v[178:181], v[8:11], v[80:83]
	v_mfma_f32_16x16x32_bf16 v[60:63], v[178:181], v[12:15], v[60:63]
	v_mfma_f32_16x16x32_bf16 v[40:43], v[182:185], v[0:3], v[40:43]
	v_mfma_f32_16x16x32_bf16 v[24:27], v[182:185], v[4:7], v[24:27]
	v_mfma_f32_16x16x32_bf16 v[56:59], v[182:185], v[8:11], v[56:59]
	v_mfma_f32_16x16x32_bf16 v[148:151], v[182:185], v[12:15], v[148:151]
	s_add_i32 s12, s12, s6
	s_add_i32 s11, s11, s9
	s_add_i32 s10, s10, s6
	s_cmpk_gt_u32 s12, 0x1ff
	s_cselect_b32 s23, 1, 0
	v_mov_b32 v250, v198
	s_nop 0
	v_and_b32_e32 v251, 15, v250
	v_bfe_u32 v156, v250, 4, 2
	v_bfe_u32 v157, v250, 6, 1
	v_bfe_u32 v158, v250, 7, 1
	v_lshl_add_u32 v158, v158, 6, s14
	v_add_u32_e32 v158, v158, v251
	v_lshl_add_u32 v157, v157, 7, s13
	v_lshl_add_u32 v159, v156, 2, v157
	v_lshlrev_b32_e32 v230, 6, v158
	v_lshlrev_b32_e32 v161, 1, v159
	v_lshl_add_u32 v228, v158, 13, v161
	v_and_b32_e32 v161, 1, v156
	v_mul_u32_u24_e32 v161, 24, v161
	v_add_u32_e32 v229, v228, v161
	s_mov_b32 s30, s92
	s_mov_b32 s31, s93
	global_load_dwordx4 v[0:3], v230, s[94:95]
	global_load_dwordx4 v[4:7], v230, s[94:95] offset:16
	global_load_dwordx4 v[8:11], v230, s[94:95] offset:32
	global_load_dwordx4 v[12:15], v230, s[94:95] offset:48
	global_load_dwordx4 v[16:19], v230, s[94:95] offset:1024
	global_load_dwordx4 v[20:23], v230, s[94:95] offset:1040
	global_load_dwordx4 v[162:165], v230, s[94:95] offset:1056
	global_load_dwordx4 v[166:169], v230, s[94:95] offset:1072
	global_load_dwordx4 v[170:173], v230, s[94:95] offset:2048
	global_load_dwordx4 v[174:177], v230, s[94:95] offset:2064
	global_load_dwordx4 v[178:181], v230, s[94:95] offset:2080
	global_load_dwordx4 v[182:185], v230, s[94:95] offset:2096
	global_load_dwordx4 v[186:189], v230, s[94:95] offset:3072
	global_load_dwordx4 v[190:193], v230, s[94:95] offset:3088
	global_load_dwordx4 v[194:197], v230, s[94:95] offset:3104
	global_load_dwordx4 v[208:211], v230, s[94:95] offset:3120
	s_waitcnt vmcnt(12)
	v_add_f32_e32 v231, v0, v1
	v_add_f32_e32 v248, v2, v3
	v_add_f32_e32 v231, v231, v248
	v_add_f32_e32 v249, v4, v5
	v_add_f32_e32 v248, v6, v7
	v_add_f32_e32 v249, v249, v248
	v_add_f32_e32 v231, v231, v249
	v_add_f32_e32 v249, v8, v9
	v_add_f32_e32 v248, v10, v11
	v_add_f32_e32 v249, v249, v248
	v_add_f32_e32 v231, v231, v249
	v_add_f32_e32 v249, v12, v13
	v_add_f32_e32 v248, v14, v15
	v_add_f32_e32 v249, v249, v248
	v_add_f32_e32 v231, v231, v249
	v_fmamk_f32 v231, v231, 0x3a800000, v199
	v_cmp_gt_f32_e32 vcc, s73, v231
	v_mul_f32_e32 v248, 0x4b800000, v231
	s_nop 0
	v_cndmask_b32_e32 v231, v231, v248, vcc
	v_rsq_f32_e32 v231, v231
	s_nop 0
	v_mul_f32_e32 v248, 0x45800000, v231
	v_cndmask_b32_e32 v231, v231, v248, vcc
	v_mul_f32_e32 v212, v128, v231
	v_mul_f32_e32 v249, v129, v231
	v_mul_f32_e32 v213, v130, v231
	v_mul_f32_e32 v248, v131, v231
	v_max_f32_e32 v212, 0, v212
	v_max_f32_e32 v249, 0, v249
	v_max_f32_e32 v213, 0, v213
	v_max_f32_e32 v248, 0, v248
	v_mul_f32_e32 v212, v212, v212
	v_mul_f32_e32 v249, v249, v249
	v_mul_f32_e32 v213, v213, v213
	v_mul_f32_e32 v248, v248, v248
	v_cvt_pk_bf16_f32 v212, v212, v249
	v_cvt_pk_bf16_f32 v213, v213, v248
	v_mul_f32_e32 v214, v116, v231
	v_mul_f32_e32 v249, v117, v231
	v_mul_f32_e32 v215, v118, v231
	v_mul_f32_e32 v248, v119, v231
	v_max_f32_e32 v214, 0, v214
	v_max_f32_e32 v249, 0, v249
	v_max_f32_e32 v215, 0, v215
	v_max_f32_e32 v248, 0, v248
	v_mul_f32_e32 v214, v214, v214
	v_mul_f32_e32 v249, v249, v249
	v_mul_f32_e32 v215, v215, v215
	v_mul_f32_e32 v248, v248, v248
	v_cvt_pk_bf16_f32 v214, v214, v249
	v_cvt_pk_bf16_f32 v215, v215, v248
	s_nop 1
	v_permlane16_swap_b32_e32 v212, v214
	v_permlane16_swap_b32_e32 v213, v215
	global_store_dwordx4 v229, v[212:215], s[30:31]
	v_mul_f32_e32 v216, v104, v231
	v_mul_f32_e32 v249, v105, v231
	v_mul_f32_e32 v217, v106, v231
	v_mul_f32_e32 v248, v107, v231
	v_max_f32_e32 v216, 0, v216
	v_max_f32_e32 v249, 0, v249
	v_max_f32_e32 v217, 0, v217
	v_max_f32_e32 v248, 0, v248
	v_mul_f32_e32 v216, v216, v216
	v_mul_f32_e32 v249, v249, v249
	v_mul_f32_e32 v217, v217, v217
	v_mul_f32_e32 v248, v248, v248
	v_cvt_pk_bf16_f32 v216, v216, v249
	v_cvt_pk_bf16_f32 v217, v217, v248
	v_mul_f32_e32 v218, v100, v231
	v_mul_f32_e32 v249, v101, v231
	v_mul_f32_e32 v219, v102, v231
	v_mul_f32_e32 v248, v103, v231
	v_max_f32_e32 v218, 0, v218
	v_max_f32_e32 v249, 0, v249
	v_max_f32_e32 v219, 0, v219
	v_max_f32_e32 v248, 0, v248
	v_mul_f32_e32 v218, v218, v218
	v_mul_f32_e32 v249, v249, v249
	v_mul_f32_e32 v219, v219, v219
	v_mul_f32_e32 v248, v248, v248
	v_cvt_pk_bf16_f32 v218, v218, v249
	v_cvt_pk_bf16_f32 v219, v219, v248
	s_nop 1
	v_permlane16_swap_b32_e32 v216, v218
	v_permlane16_swap_b32_e32 v217, v219
	global_store_dwordx4 v229, v[216:219], s[30:31] offset:64
	v_mul_f32_e32 v220, v52, v231
	v_mul_f32_e32 v249, v53, v231
	v_mul_f32_e32 v221, v54, v231
	v_mul_f32_e32 v248, v55, v231
	v_max_f32_e32 v220, 0, v220
	v_max_f32_e32 v249, 0, v249
	v_max_f32_e32 v221, 0, v221
	v_max_f32_e32 v248, 0, v248
	v_mul_f32_e32 v220, v220, v220
	v_mul_f32_e32 v249, v249, v249
	v_mul_f32_e32 v221, v221, v221
	v_mul_f32_e32 v248, v248, v248
	v_cvt_pk_bf16_f32 v220, v220, v249
	v_cvt_pk_bf16_f32 v221, v221, v248
	v_mul_f32_e32 v222, v48, v231
	v_mul_f32_e32 v249, v49, v231
	v_mul_f32_e32 v223, v50, v231
	v_mul_f32_e32 v248, v51, v231
	v_max_f32_e32 v222, 0, v222
	v_max_f32_e32 v249, 0, v249
	v_max_f32_e32 v223, 0, v223
	v_max_f32_e32 v248, 0, v248
	v_mul_f32_e32 v222, v222, v222
	v_mul_f32_e32 v249, v249, v249
	v_mul_f32_e32 v223, v223, v223
	v_mul_f32_e32 v248, v248, v248
	v_cvt_pk_bf16_f32 v222, v222, v249
	v_cvt_pk_bf16_f32 v223, v223, v248
	s_nop 1
	v_permlane16_swap_b32_e32 v220, v222
	v_permlane16_swap_b32_e32 v221, v223
	global_store_dwordx4 v229, v[220:223], s[30:31] offset:128
	v_mul_f32_e32 v224, v44, v231
	v_mul_f32_e32 v249, v45, v231
	v_mul_f32_e32 v225, v46, v231
	v_mul_f32_e32 v248, v47, v231
	v_max_f32_e32 v224, 0, v224
	v_max_f32_e32 v249, 0, v249
	v_max_f32_e32 v225, 0, v225
	v_max_f32_e32 v248, 0, v248
	v_mul_f32_e32 v224, v224, v224
	v_mul_f32_e32 v249, v249, v249
	v_mul_f32_e32 v225, v225, v225
	v_mul_f32_e32 v248, v248, v248
	v_cvt_pk_bf16_f32 v224, v224, v249
	v_cvt_pk_bf16_f32 v225, v225, v248
	v_mul_f32_e32 v226, v40, v231
	v_mul_f32_e32 v249, v41, v231
	v_mul_f32_e32 v227, v42, v231
	v_mul_f32_e32 v248, v43, v231
	v_max_f32_e32 v226, 0, v226
	v_max_f32_e32 v249, 0, v249
	v_max_f32_e32 v227, 0, v227
	v_max_f32_e32 v248, 0, v248
	v_mul_f32_e32 v226, v226, v226
	v_mul_f32_e32 v249, v249, v249
	v_mul_f32_e32 v227, v227, v227
	v_mul_f32_e32 v248, v248, v248
	v_cvt_pk_bf16_f32 v226, v226, v249
	v_cvt_pk_bf16_f32 v227, v227, v248
	s_nop 1
	v_permlane16_swap_b32_e32 v224, v226
	v_permlane16_swap_b32_e32 v225, v227
	global_store_dwordx4 v229, v[224:227], s[30:31] offset:192
	s_add_u32 s30, s30, 0x20000
	s_addc_u32 s31, s31, 0
	s_waitcnt vmcnt(12)
	v_add_f32_e32 v231, v16, v17
	v_add_f32_e32 v248, v18, v19
	v_add_f32_e32 v231, v231, v248
	v_add_f32_e32 v249, v20, v21
	v_add_f32_e32 v248, v22, v23
	v_add_f32_e32 v249, v249, v248
	v_add_f32_e32 v231, v231, v249
	v_add_f32_e32 v249, v162, v163
	v_add_f32_e32 v248, v164, v165
	v_add_f32_e32 v249, v249, v248
	v_add_f32_e32 v231, v231, v249
	v_add_f32_e32 v249, v166, v167
	v_add_f32_e32 v248, v168, v169
	v_add_f32_e32 v249, v249, v248
	v_add_f32_e32 v231, v231, v249
	v_fmamk_f32 v231, v231, 0x3a800000, v199
	v_cmp_gt_f32_e32 vcc, s73, v231
	v_mul_f32_e32 v248, 0x4b800000, v231
	s_nop 0
	v_cndmask_b32_e32 v231, v231, v248, vcc
	v_rsq_f32_e32 v231, v231
	s_nop 0
	v_mul_f32_e32 v248, 0x45800000, v231
	v_cndmask_b32_e32 v231, v231, v248, vcc
	v_mul_f32_e32 v212, v96, v231
	v_mul_f32_e32 v249, v97, v231
	v_mul_f32_e32 v213, v98, v231
	v_mul_f32_e32 v248, v99, v231
	v_max_f32_e32 v212, 0, v212
	v_max_f32_e32 v249, 0, v249
	v_max_f32_e32 v213, 0, v213
	v_max_f32_e32 v248, 0, v248
	v_mul_f32_e32 v212, v212, v212
	v_mul_f32_e32 v249, v249, v249
	v_mul_f32_e32 v213, v213, v213
	v_mul_f32_e32 v248, v248, v248
	v_cvt_pk_bf16_f32 v212, v212, v249
	v_cvt_pk_bf16_f32 v213, v213, v248
	v_mul_f32_e32 v214, v92, v231
	v_mul_f32_e32 v249, v93, v231
	v_mul_f32_e32 v215, v94, v231
	v_mul_f32_e32 v248, v95, v231
	v_max_f32_e32 v214, 0, v214
	v_max_f32_e32 v249, 0, v249
	v_max_f32_e32 v215, 0, v215
	v_max_f32_e32 v248, 0, v248
	v_mul_f32_e32 v214, v214, v214
	v_mul_f32_e32 v249, v249, v249
	v_mul_f32_e32 v215, v215, v215
	v_mul_f32_e32 v248, v248, v248
	v_cvt_pk_bf16_f32 v214, v214, v249
	v_cvt_pk_bf16_f32 v215, v215, v248
	s_nop 1
	v_permlane16_swap_b32_e32 v212, v214
	v_permlane16_swap_b32_e32 v213, v215
	global_store_dwordx4 v229, v[212:215], s[30:31]
	v_mul_f32_e32 v216, v88, v231
	v_mul_f32_e32 v249, v89, v231
	v_mul_f32_e32 v217, v90, v231
	v_mul_f32_e32 v248, v91, v231
	v_max_f32_e32 v216, 0, v216
	v_max_f32_e32 v249, 0, v249
	v_max_f32_e32 v217, 0, v217
	v_max_f32_e32 v248, 0, v248
	v_mul_f32_e32 v216, v216, v216
	v_mul_f32_e32 v249, v249, v249
	v_mul_f32_e32 v217, v217, v217
	v_mul_f32_e32 v248, v248, v248
	v_cvt_pk_bf16_f32 v216, v216, v249
	v_cvt_pk_bf16_f32 v217, v217, v248
	v_mul_f32_e32 v218, v84, v231
	v_mul_f32_e32 v249, v85, v231
	v_mul_f32_e32 v219, v86, v231
	v_mul_f32_e32 v248, v87, v231
	v_max_f32_e32 v218, 0, v218
	v_max_f32_e32 v249, 0, v249
	v_max_f32_e32 v219, 0, v219
	v_max_f32_e32 v248, 0, v248
	v_mul_f32_e32 v218, v218, v218
	v_mul_f32_e32 v249, v249, v249
	v_mul_f32_e32 v219, v219, v219
	v_mul_f32_e32 v248, v248, v248
	v_cvt_pk_bf16_f32 v218, v218, v249
	v_cvt_pk_bf16_f32 v219, v219, v248
	s_nop 1
	v_permlane16_swap_b32_e32 v216, v218
	v_permlane16_swap_b32_e32 v217, v219
	global_store_dwordx4 v229, v[216:219], s[30:31] offset:64
	v_mul_f32_e32 v220, v36, v231
	v_mul_f32_e32 v249, v37, v231
	v_mul_f32_e32 v221, v38, v231
	v_mul_f32_e32 v248, v39, v231
	v_max_f32_e32 v220, 0, v220
	v_max_f32_e32 v249, 0, v249
	v_max_f32_e32 v221, 0, v221
	v_max_f32_e32 v248, 0, v248
	v_mul_f32_e32 v220, v220, v220
	v_mul_f32_e32 v249, v249, v249
	v_mul_f32_e32 v221, v221, v221
	v_mul_f32_e32 v248, v248, v248
	v_cvt_pk_bf16_f32 v220, v220, v249
	v_cvt_pk_bf16_f32 v221, v221, v248
	v_mul_f32_e32 v222, v32, v231
	v_mul_f32_e32 v249, v33, v231
	v_mul_f32_e32 v223, v34, v231
	v_mul_f32_e32 v248, v35, v231
	v_max_f32_e32 v222, 0, v222
	v_max_f32_e32 v249, 0, v249
	v_max_f32_e32 v223, 0, v223
	v_max_f32_e32 v248, 0, v248
	v_mul_f32_e32 v222, v222, v222
	v_mul_f32_e32 v249, v249, v249
	v_mul_f32_e32 v223, v223, v223
	v_mul_f32_e32 v248, v248, v248
	v_cvt_pk_bf16_f32 v222, v222, v249
	v_cvt_pk_bf16_f32 v223, v223, v248
	s_nop 1
	v_permlane16_swap_b32_e32 v220, v222
	v_permlane16_swap_b32_e32 v221, v223
	global_store_dwordx4 v229, v[220:223], s[30:31] offset:128
	v_mul_f32_e32 v224, v28, v231
	v_mul_f32_e32 v249, v29, v231
	v_mul_f32_e32 v225, v30, v231
	v_mul_f32_e32 v248, v31, v231
	v_max_f32_e32 v224, 0, v224
	v_max_f32_e32 v249, 0, v249
	v_max_f32_e32 v225, 0, v225
	v_max_f32_e32 v248, 0, v248
	v_mul_f32_e32 v224, v224, v224
	v_mul_f32_e32 v249, v249, v249
	v_mul_f32_e32 v225, v225, v225
	v_mul_f32_e32 v248, v248, v248
	v_cvt_pk_bf16_f32 v224, v224, v249
	v_cvt_pk_bf16_f32 v225, v225, v248
	v_mul_f32_e32 v226, v24, v231
	v_mul_f32_e32 v249, v25, v231
	v_mul_f32_e32 v227, v26, v231
	v_mul_f32_e32 v248, v27, v231
	v_max_f32_e32 v226, 0, v226
	v_max_f32_e32 v249, 0, v249
	v_max_f32_e32 v227, 0, v227
	v_max_f32_e32 v248, 0, v248
	v_mul_f32_e32 v226, v226, v226
	v_mul_f32_e32 v249, v249, v249
	v_mul_f32_e32 v227, v227, v227
	v_mul_f32_e32 v248, v248, v248
	v_cvt_pk_bf16_f32 v226, v226, v249
	v_cvt_pk_bf16_f32 v227, v227, v248
	s_nop 1
	v_permlane16_swap_b32_e32 v224, v226
	v_permlane16_swap_b32_e32 v225, v227
	global_store_dwordx4 v229, v[224:227], s[30:31] offset:192
	s_add_u32 s30, s30, 0x20000
	s_addc_u32 s31, s31, 0
	s_waitcnt vmcnt(12)
	v_add_f32_e32 v231, v170, v171
	v_add_f32_e32 v248, v172, v173
	v_add_f32_e32 v231, v231, v248
	v_add_f32_e32 v249, v174, v175
	v_add_f32_e32 v248, v176, v177
	v_add_f32_e32 v249, v249, v248
	v_add_f32_e32 v231, v231, v249
	v_add_f32_e32 v249, v178, v179
	v_add_f32_e32 v248, v180, v181
	v_add_f32_e32 v249, v249, v248
	v_add_f32_e32 v231, v231, v249
	v_add_f32_e32 v249, v182, v183
	v_add_f32_e32 v248, v184, v185
	v_add_f32_e32 v249, v249, v248
	v_add_f32_e32 v231, v231, v249
	v_fmamk_f32 v231, v231, 0x3a800000, v199
	v_cmp_gt_f32_e32 vcc, s73, v231
	v_mul_f32_e32 v248, 0x4b800000, v231
	s_nop 0
	v_cndmask_b32_e32 v231, v231, v248, vcc
	v_rsq_f32_e32 v231, v231
	s_nop 0
	v_mul_f32_e32 v248, 0x45800000, v231
	v_cndmask_b32_e32 v231, v231, v248, vcc
	v_mul_f32_e32 v212, v108, v231
	v_mul_f32_e32 v249, v109, v231
	v_mul_f32_e32 v213, v110, v231
	v_mul_f32_e32 v248, v111, v231
	v_max_f32_e32 v212, 0, v212
	v_max_f32_e32 v249, 0, v249
	v_max_f32_e32 v213, 0, v213
	v_max_f32_e32 v248, 0, v248
	v_mul_f32_e32 v212, v212, v212
	v_mul_f32_e32 v249, v249, v249
	v_mul_f32_e32 v213, v213, v213
	v_mul_f32_e32 v248, v248, v248
	v_cvt_pk_bf16_f32 v212, v212, v249
	v_cvt_pk_bf16_f32 v213, v213, v248
	v_mul_f32_e32 v214, v112, v231
	v_mul_f32_e32 v249, v113, v231
	v_mul_f32_e32 v215, v114, v231
	v_mul_f32_e32 v248, v115, v231
	v_max_f32_e32 v214, 0, v214
	v_max_f32_e32 v249, 0, v249
	v_max_f32_e32 v215, 0, v215
	v_max_f32_e32 v248, 0, v248
	v_mul_f32_e32 v214, v214, v214
	v_mul_f32_e32 v249, v249, v249
	v_mul_f32_e32 v215, v215, v215
	v_mul_f32_e32 v248, v248, v248
	v_cvt_pk_bf16_f32 v214, v214, v249
	v_cvt_pk_bf16_f32 v215, v215, v248
	s_nop 1
	v_permlane16_swap_b32_e32 v212, v214
	v_permlane16_swap_b32_e32 v213, v215
	global_store_dwordx4 v229, v[212:215], s[30:31]
	v_mul_f32_e32 v216, v120, v231
	v_mul_f32_e32 v249, v121, v231
	v_mul_f32_e32 v217, v122, v231
	v_mul_f32_e32 v248, v123, v231
	v_max_f32_e32 v216, 0, v216
	v_max_f32_e32 v249, 0, v249
	v_max_f32_e32 v217, 0, v217
	v_max_f32_e32 v248, 0, v248
	v_mul_f32_e32 v216, v216, v216
	v_mul_f32_e32 v249, v249, v249
	v_mul_f32_e32 v217, v217, v217
	v_mul_f32_e32 v248, v248, v248
	v_cvt_pk_bf16_f32 v216, v216, v249
	v_cvt_pk_bf16_f32 v217, v217, v248
	v_mul_f32_e32 v218, v124, v231
	v_mul_f32_e32 v249, v125, v231
	v_mul_f32_e32 v219, v126, v231
	v_mul_f32_e32 v248, v127, v231
	v_max_f32_e32 v218, 0, v218
	v_max_f32_e32 v249, 0, v249
	v_max_f32_e32 v219, 0, v219
	v_max_f32_e32 v248, 0, v248
	v_mul_f32_e32 v218, v218, v218
	v_mul_f32_e32 v249, v249, v249
	v_mul_f32_e32 v219, v219, v219
	v_mul_f32_e32 v248, v248, v248
	v_cvt_pk_bf16_f32 v218, v218, v249
	v_cvt_pk_bf16_f32 v219, v219, v248
	s_nop 1
	v_permlane16_swap_b32_e32 v216, v218
	v_permlane16_swap_b32_e32 v217, v219
	global_store_dwordx4 v229, v[216:219], s[30:31] offset:64
	v_mul_f32_e32 v220, v64, v231
	v_mul_f32_e32 v249, v65, v231
	v_mul_f32_e32 v221, v66, v231
	v_mul_f32_e32 v248, v67, v231
	v_max_f32_e32 v220, 0, v220
	v_max_f32_e32 v249, 0, v249
	v_max_f32_e32 v221, 0, v221
	v_max_f32_e32 v248, 0, v248
	v_mul_f32_e32 v220, v220, v220
	v_mul_f32_e32 v249, v249, v249
	v_mul_f32_e32 v221, v221, v221
	v_mul_f32_e32 v248, v248, v248
	v_cvt_pk_bf16_f32 v220, v220, v249
	v_cvt_pk_bf16_f32 v221, v221, v248
	v_mul_f32_e32 v222, v68, v231
	v_mul_f32_e32 v249, v69, v231
	v_mul_f32_e32 v223, v70, v231
	v_mul_f32_e32 v248, v71, v231
	v_max_f32_e32 v222, 0, v222
	v_max_f32_e32 v249, 0, v249
	v_max_f32_e32 v223, 0, v223
	v_max_f32_e32 v248, 0, v248
	v_mul_f32_e32 v222, v222, v222
	v_mul_f32_e32 v249, v249, v249
	v_mul_f32_e32 v223, v223, v223
	v_mul_f32_e32 v248, v248, v248
	v_cvt_pk_bf16_f32 v222, v222, v249
	v_cvt_pk_bf16_f32 v223, v223, v248
	s_nop 1
	v_permlane16_swap_b32_e32 v220, v222
	v_permlane16_swap_b32_e32 v221, v223
	global_store_dwordx4 v229, v[220:223], s[30:31] offset:128
	v_mul_f32_e32 v224, v80, v231
	v_mul_f32_e32 v249, v81, v231
	v_mul_f32_e32 v225, v82, v231
	v_mul_f32_e32 v248, v83, v231
	v_max_f32_e32 v224, 0, v224
	v_max_f32_e32 v249, 0, v249
	v_max_f32_e32 v225, 0, v225
	v_max_f32_e32 v248, 0, v248
	v_mul_f32_e32 v224, v224, v224
	v_mul_f32_e32 v249, v249, v249
	v_mul_f32_e32 v225, v225, v225
	v_mul_f32_e32 v248, v248, v248
	v_cvt_pk_bf16_f32 v224, v224, v249
	v_cvt_pk_bf16_f32 v225, v225, v248
	v_mul_f32_e32 v226, v56, v231
	v_mul_f32_e32 v249, v57, v231
	v_mul_f32_e32 v227, v58, v231
	v_mul_f32_e32 v248, v59, v231
	v_max_f32_e32 v226, 0, v226
	v_max_f32_e32 v249, 0, v249
	v_max_f32_e32 v227, 0, v227
	v_max_f32_e32 v248, 0, v248
	v_mul_f32_e32 v226, v226, v226
	v_mul_f32_e32 v249, v249, v249
	v_mul_f32_e32 v227, v227, v227
	v_mul_f32_e32 v248, v248, v248
	v_cvt_pk_bf16_f32 v226, v226, v249
	v_cvt_pk_bf16_f32 v227, v227, v248
	s_nop 1
	v_permlane16_swap_b32_e32 v224, v226
	v_permlane16_swap_b32_e32 v225, v227
	global_store_dwordx4 v229, v[224:227], s[30:31] offset:192
	s_add_u32 s30, s30, 0x20000
	s_addc_u32 s31, s31, 0
	s_waitcnt vmcnt(12)
	v_add_f32_e32 v231, v186, v187
	v_add_f32_e32 v248, v188, v189
	v_add_f32_e32 v231, v231, v248
	v_add_f32_e32 v249, v190, v191
	v_add_f32_e32 v248, v192, v193
	v_add_f32_e32 v249, v249, v248
	v_add_f32_e32 v231, v231, v249
	v_add_f32_e32 v249, v194, v195
	v_add_f32_e32 v248, v196, v197
	v_add_f32_e32 v249, v249, v248
	v_add_f32_e32 v231, v231, v249
	v_add_f32_e32 v249, v208, v209
	v_add_f32_e32 v248, v210, v211
	v_add_f32_e32 v249, v249, v248
	v_add_f32_e32 v231, v231, v249
	v_fmamk_f32 v231, v231, 0x3a800000, v199
	v_cmp_gt_f32_e32 vcc, s73, v231
	v_mul_f32_e32 v248, 0x4b800000, v231
	s_nop 0
	v_cndmask_b32_e32 v231, v231, v248, vcc
	v_rsq_f32_e32 v231, v231
	s_nop 0
	v_mul_f32_e32 v248, 0x45800000, v231
	v_cndmask_b32_e32 v231, v231, v248, vcc
	v_mul_f32_e32 v212, v132, v231
	v_mul_f32_e32 v249, v133, v231
	v_mul_f32_e32 v213, v134, v231
	v_mul_f32_e32 v248, v135, v231
	v_max_f32_e32 v212, 0, v212
	v_max_f32_e32 v249, 0, v249
	v_max_f32_e32 v213, 0, v213
	v_max_f32_e32 v248, 0, v248
	v_mul_f32_e32 v212, v212, v212
	v_mul_f32_e32 v249, v249, v249
	v_mul_f32_e32 v213, v213, v213
	v_mul_f32_e32 v248, v248, v248
	v_cvt_pk_bf16_f32 v212, v212, v249
	v_cvt_pk_bf16_f32 v213, v213, v248
	v_mul_f32_e32 v214, v136, v231
	v_mul_f32_e32 v249, v137, v231
	v_mul_f32_e32 v215, v138, v231
	v_mul_f32_e32 v248, v139, v231
	v_max_f32_e32 v214, 0, v214
	v_max_f32_e32 v249, 0, v249
	v_max_f32_e32 v215, 0, v215
	v_max_f32_e32 v248, 0, v248
	v_mul_f32_e32 v214, v214, v214
	v_mul_f32_e32 v249, v249, v249
	v_mul_f32_e32 v215, v215, v215
	v_mul_f32_e32 v248, v248, v248
	v_cvt_pk_bf16_f32 v214, v214, v249
	v_cvt_pk_bf16_f32 v215, v215, v248
	s_nop 1
	v_permlane16_swap_b32_e32 v212, v214
	v_permlane16_swap_b32_e32 v213, v215
	global_store_dwordx4 v229, v[212:215], s[30:31]
	v_mul_f32_e32 v216, v140, v231
	v_mul_f32_e32 v249, v141, v231
	v_mul_f32_e32 v217, v142, v231
	v_mul_f32_e32 v248, v143, v231
	v_max_f32_e32 v216, 0, v216
	v_max_f32_e32 v249, 0, v249
	v_max_f32_e32 v217, 0, v217
	v_max_f32_e32 v248, 0, v248
	v_mul_f32_e32 v216, v216, v216
	v_mul_f32_e32 v249, v249, v249
	v_mul_f32_e32 v217, v217, v217
	v_mul_f32_e32 v248, v248, v248
	v_cvt_pk_bf16_f32 v216, v216, v249
	v_cvt_pk_bf16_f32 v217, v217, v248
	v_mul_f32_e32 v218, v144, v231
	v_mul_f32_e32 v249, v145, v231
	v_mul_f32_e32 v219, v146, v231
	v_mul_f32_e32 v248, v147, v231
	v_max_f32_e32 v218, 0, v218
	v_max_f32_e32 v249, 0, v249
	v_max_f32_e32 v219, 0, v219
	v_max_f32_e32 v248, 0, v248
	v_mul_f32_e32 v218, v218, v218
	v_mul_f32_e32 v249, v249, v249
	v_mul_f32_e32 v219, v219, v219
	v_mul_f32_e32 v248, v248, v248
	v_cvt_pk_bf16_f32 v218, v218, v249
	v_cvt_pk_bf16_f32 v219, v219, v248
	s_nop 1
	v_permlane16_swap_b32_e32 v216, v218
	v_permlane16_swap_b32_e32 v217, v219
	global_store_dwordx4 v229, v[216:219], s[30:31] offset:64
	v_mul_f32_e32 v220, v76, v231
	v_mul_f32_e32 v249, v77, v231
	v_mul_f32_e32 v221, v78, v231
	v_mul_f32_e32 v248, v79, v231
	v_max_f32_e32 v220, 0, v220
	v_max_f32_e32 v249, 0, v249
	v_max_f32_e32 v221, 0, v221
	v_max_f32_e32 v248, 0, v248
	v_mul_f32_e32 v220, v220, v220
	v_mul_f32_e32 v249, v249, v249
	v_mul_f32_e32 v221, v221, v221
	v_mul_f32_e32 v248, v248, v248
	v_cvt_pk_bf16_f32 v220, v220, v249
	v_cvt_pk_bf16_f32 v221, v221, v248
	v_mul_f32_e32 v222, v72, v231
	v_mul_f32_e32 v249, v73, v231
	v_mul_f32_e32 v223, v74, v231
	v_mul_f32_e32 v248, v75, v231
	v_max_f32_e32 v222, 0, v222
	v_max_f32_e32 v249, 0, v249
	v_max_f32_e32 v223, 0, v223
	v_max_f32_e32 v248, 0, v248
	v_mul_f32_e32 v222, v222, v222
	v_mul_f32_e32 v249, v249, v249
	v_mul_f32_e32 v223, v223, v223
	v_mul_f32_e32 v248, v248, v248
	v_cvt_pk_bf16_f32 v222, v222, v249
	v_cvt_pk_bf16_f32 v223, v223, v248
	s_nop 1
	v_permlane16_swap_b32_e32 v220, v222
	v_permlane16_swap_b32_e32 v221, v223
	global_store_dwordx4 v229, v[220:223], s[30:31] offset:128
	v_mul_f32_e32 v224, v60, v231
	v_mul_f32_e32 v249, v61, v231
	v_mul_f32_e32 v225, v62, v231
	v_mul_f32_e32 v248, v63, v231
	v_max_f32_e32 v224, 0, v224
	v_max_f32_e32 v249, 0, v249
	v_max_f32_e32 v225, 0, v225
	v_max_f32_e32 v248, 0, v248
	v_mul_f32_e32 v224, v224, v224
	v_mul_f32_e32 v249, v249, v249
	v_mul_f32_e32 v225, v225, v225
	v_mul_f32_e32 v248, v248, v248
	v_cvt_pk_bf16_f32 v224, v224, v249
	v_cvt_pk_bf16_f32 v225, v225, v248
	v_mul_f32_e32 v226, v148, v231
	v_mul_f32_e32 v249, v149, v231
	v_mul_f32_e32 v227, v150, v231
	v_mul_f32_e32 v248, v151, v231
	v_max_f32_e32 v226, 0, v226
	v_max_f32_e32 v249, 0, v249
	v_max_f32_e32 v227, 0, v227
	v_max_f32_e32 v248, 0, v248
	v_mul_f32_e32 v226, v226, v226
	v_mul_f32_e32 v249, v249, v249
	v_mul_f32_e32 v227, v227, v227
	v_mul_f32_e32 v248, v248, v248
	v_cvt_pk_bf16_f32 v226, v226, v249
	v_cvt_pk_bf16_f32 v227, v227, v248
	s_nop 1
	v_permlane16_swap_b32_e32 v224, v226
	v_permlane16_swap_b32_e32 v225, v227
	global_store_dwordx4 v229, v[224:227], s[30:31] offset:192
	s_add_u32 s30, s30, 0x20000
	s_addc_u32 s31, s31, 0
	s_cmp_lg_u32 s23, 0
	s_cbranch_scc0 .LBB0_13

.LBB0_51:
	s_or_b64 exec, exec, s[4:5]
	s_waitcnt lgkmcnt(0)
	s_barrier
	ds_read_b32 v0, v201
	s_movk_i32 s4, 0x200
	s_waitcnt lgkmcnt(0)
	v_cmp_gt_i32_e32 vcc, s4, v0
	v_readfirstlane_b32 s16, v0
	s_mov_b64 s[4:5], -1
	s_cbranch_vccz .LBB0_46
	s_bfe_u32 s17, s16, 0x30002
	s_and_b32 s19, s16, 3
	s_ashr_i32 s11, s16, 5
	s_lshl_b32 s4, s19, 14
	s_lshl_b32 s5, s17, 16
	s_sub_i32 s14, 15, s11
	s_or_b32 s4, s5, s4
	v_readlane_b32 s5, v253, 34
	s_add_u32 s4, s5, s4
	v_readlane_b32 s5, v253, 35
	v_mov_b32 v137, v198
	s_addc_u32 s5, s5, 0
	s_lshl_b32 s10, s14, 8
	v_and_b32_e32 v11, 0xffffffc0, v137
	v_and_b32_e32 v143, 15, v137
	v_add_u32_e32 v0, s10, v11
	v_or_b32_e32 v130, v0, v143
	v_ashrrev_i32_e32 v131, 31, v130
	s_lshl_b32 s84, s17, 12
	v_ashrrev_i32_e32 v1, 31, v0
	v_lshl_add_u64 v[2:3], v[130:131], 2, s[4:5]
	global_load_dword v131, v[2:3], off
	global_load_dword v155, v[2:3], off offset:64
	global_load_dword v168, v[2:3], off offset:128
	global_load_dword v169, v[2:3], off offset:192
	v_lshl_add_u64 v[128:129], v[0:1], 0, s[84:85]
	v_bfe_u32 v2, v137, 3, 3
	v_or_b32_e32 v3, v128, v2
	v_mov_b64_e32 v[8:9], s[92:93]
	v_mad_u64_u32 v[4:5], s[12:13], v3, s63, v[8:9]
	v_mad_i32_i24 v5, v129, s63, v5
	s_lshl_b32 s12, s19, 7
	s_mov_b32 s13, s85
	v_lshlrev_b32_e32 v3, 4, v137
	v_lshl_add_u64 v[4:5], v[4:5], 0, s[12:13]
	v_and_b32_e32 v152, 0x70, v3
	v_lshl_add_u64 v[4:5], v[4:5], 0, v[152:153]
	v_add_co_u32_e32 v4, vcc, s64, v4
	v_xor_b32_e32 v12, v2, v137
	s_nop 0
	v_addc_co_u32_e32 v5, vcc, 0, v5, vcc
	global_load_dwordx4 v[64:67], v[4:5], off offset:512
	v_add_co_u32_e32 v96, vcc, 0xc000, v4
	s_nop 1
	v_addc_co_u32_e32 v97, vcc, 0, v5, vcc
	global_load_dwordx4 v[68:71], v[96:97], off offset:512
	v_add_co_u32_e32 v98, vcc, 0x18000, v4
	s_nop 1
	v_addc_co_u32_e32 v99, vcc, 0, v5, vcc
	global_load_dwordx4 v[72:75], v[98:99], off offset:512
	v_add_co_u32_e32 v100, vcc, 0x24000, v4
	s_nop 1
	v_addc_co_u32_e32 v101, vcc, 0, v5, vcc
	global_load_dwordx4 v[76:79], v[100:101], off offset:512
	v_add_co_u32_e32 v102, vcc, 0x30000, v4
	s_nop 1
	v_addc_co_u32_e32 v103, vcc, 0, v5, vcc
	global_load_dwordx4 v[80:83], v[102:103], off offset:512
	v_add_co_u32_e32 v104, vcc, 0x3c000, v4
	s_nop 1
	v_addc_co_u32_e32 v105, vcc, 0, v5, vcc
	global_load_dwordx4 v[84:87], v[104:105], off offset:512
	v_add_co_u32_e32 v106, vcc, 0x48000, v4
	s_nop 1
	v_addc_co_u32_e32 v107, vcc, 0, v5, vcc
	global_load_dwordx4 v[88:91], v[106:107], off offset:512
	v_add_co_u32_e32 v108, vcc, 0x54000, v4
	s_nop 1
	v_addc_co_u32_e32 v109, vcc, 0, v5, vcc
	global_load_dwordx4 v[92:95], v[108:109], off offset:512
	s_waitcnt vmcnt(0)
	v_lshlrev_b32_e32 v12, 4, v12
	v_or_b32_e32 v3, v2, v11
	v_and_b32_e32 v12, 0x70, v12
	v_lshl_or_b32 v3, v3, 7, v12
	v_ashrrev_i32_e32 v10, 6, v137
	v_mov_b32_e32 v171, 0
	ds_write_b128 v3, v[64:67] offset:32768
	v_or_b32_e32 v3, 8, v2
	v_or_b32_e32 v4, v128, v3
	v_mad_u64_u32 v[4:5], s[20:21], v4, s63, v[8:9]
	v_mad_i32_i24 v5, v129, s63, v5
	v_lshl_add_u64 v[4:5], v[4:5], 0, s[12:13]
	v_lshl_add_u64 v[4:5], v[4:5], 0, v[152:153]
	v_add_co_u32_e32 v4, vcc, s64, v4
	v_or_b32_e32 v3, v3, v11
	s_nop 0
	v_addc_co_u32_e32 v5, vcc, 0, v5, vcc
	v_lshl_or_b32 v3, v3, 7, v12
	ds_write_b128 v3, v[68:71] offset:32768
	v_or_b32_e32 v3, 16, v2
	v_or_b32_e32 v4, v128, v3
	v_mad_u64_u32 v[4:5], s[20:21], v4, s63, v[8:9]
	v_mad_i32_i24 v5, v129, s63, v5
	v_lshl_add_u64 v[4:5], v[4:5], 0, s[12:13]
	v_lshl_add_u64 v[4:5], v[4:5], 0, v[152:153]
	v_add_co_u32_e32 v4, vcc, s64, v4
	v_or_b32_e32 v3, v3, v11
	s_nop 0
	v_addc_co_u32_e32 v5, vcc, 0, v5, vcc
	v_lshl_or_b32 v3, v3, 7, v12
	ds_write_b128 v3, v[72:75] offset:32768
	v_or_b32_e32 v3, 24, v2
	v_or_b32_e32 v4, v128, v3
	v_mad_u64_u32 v[4:5], s[20:21], v4, s63, v[8:9]
	v_mad_i32_i24 v5, v129, s63, v5
	v_lshl_add_u64 v[4:5], v[4:5], 0, s[12:13]
	v_lshl_add_u64 v[4:5], v[4:5], 0, v[152:153]
	v_add_co_u32_e32 v4, vcc, s64, v4
	v_or_b32_e32 v3, v3, v11
	s_nop 0
	v_addc_co_u32_e32 v5, vcc, 0, v5, vcc
	v_lshl_or_b32 v3, v3, 7, v12
	ds_write_b128 v3, v[76:79] offset:32768
	v_or_b32_e32 v3, 32, v2
	v_or_b32_e32 v4, v128, v3
	v_mad_u64_u32 v[4:5], s[20:21], v4, s63, v[8:9]
	v_mad_i32_i24 v5, v129, s63, v5
	v_lshl_add_u64 v[4:5], v[4:5], 0, s[12:13]
	v_lshl_add_u64 v[4:5], v[4:5], 0, v[152:153]
	v_add_co_u32_e32 v4, vcc, s64, v4
	v_or_b32_e32 v3, v3, v11
	s_nop 0
	v_addc_co_u32_e32 v5, vcc, 0, v5, vcc
	v_lshl_or_b32 v3, v3, 7, v12
	ds_write_b128 v3, v[80:83] offset:32768
	v_or_b32_e32 v3, 40, v2
	v_or_b32_e32 v4, v128, v3
	v_mad_u64_u32 v[4:5], s[20:21], v4, s63, v[8:9]
	v_mad_i32_i24 v5, v129, s63, v5
	v_lshl_add_u64 v[4:5], v[4:5], 0, s[12:13]
	v_lshl_add_u64 v[4:5], v[4:5], 0, v[152:153]
	v_add_co_u32_e32 v4, vcc, s64, v4
	v_or_b32_e32 v3, v3, v11
	s_nop 0
	v_addc_co_u32_e32 v5, vcc, 0, v5, vcc
	v_lshl_or_b32 v3, v3, 7, v12
	ds_write_b128 v3, v[84:87] offset:32768
	v_or_b32_e32 v3, 48, v2
	v_or_b32_e32 v4, v128, v3
	v_mad_u64_u32 v[4:5], s[20:21], v4, s63, v[8:9]
	v_mad_i32_i24 v5, v129, s63, v5
	v_lshl_add_u64 v[4:5], v[4:5], 0, s[12:13]
	v_lshl_add_u64 v[4:5], v[4:5], 0, v[152:153]
	v_add_co_u32_e32 v4, vcc, s64, v4
	v_or_b32_e32 v3, v3, v11
	s_nop 0
	v_addc_co_u32_e32 v5, vcc, 0, v5, vcc
	v_lshl_or_b32 v3, v3, 7, v12
	ds_write_b128 v3, v[88:91] offset:32768
	v_or_b32_e32 v3, 56, v2
	v_or_b32_e32 v4, v128, v3
	v_mad_u64_u32 v[4:5], s[20:21], v4, s63, v[8:9]
	v_mad_i32_i24 v5, v129, s63, v5
	v_lshl_add_u64 v[4:5], v[4:5], 0, s[12:13]
	v_lshl_add_u64 v[4:5], v[4:5], 0, v[152:153]
	v_add_co_u32_e32 v4, vcc, s64, v4
	s_lshl_b32 s20, s14, 2
	s_nop 0
	v_addc_co_u32_e32 v5, vcc, 0, v5, vcc
	v_or_b32_e32 v3, v3, v11
	v_add_u32_e32 v170, s20, v10
	v_lshl_or_b32 v3, v3, 7, v12
	v_cmp_lt_i32_e32 vcc, 0, v170
	ds_write_b128 v3, v[92:95] offset:32768
	s_waitcnt lgkmcnt(0)
	s_barrier
	v_and_b32_e32 v3, 63, v137
	v_lshlrev_b32_e32 v4, 8, v3
	global_load_dword v4, v4, s[4:5] offset:252
	v_lshl_add_u64 v[0:1], v[0:1], 2, s[4:5]
	global_load_dword v0, v[0:1], off
	s_mov_b32 s11, s85
	s_lshl_b64 s[10:11], s[10:11], 2
	s_add_u32 s10, s4, s10
	s_addc_u32 s11, s5, s11
	global_load_dword v1, v153, s[10:11]
	s_lshl_b32 s18, s19, 6
	v_readfirstlane_b32 s11, v170
	s_waitcnt vmcnt(0)
	v_sub_f32_e32 v5, v0, v4
	v_cmp_le_f32_e64 s[14:15], s71, v5
	s_lshl_b64 s[12:13], 1, s11
	s_add_u32 s12, s12, -1
	s_addc_u32 s13, s13, -1
	s_and_b64 s[12:13], s[12:13], s[14:15]
	s_ff1_i32_b64 s10, s[12:13]
	s_cmp_lg_u64 s[12:13], 0
	s_cselect_b32 s10, s10, s11
	v_mov_b32_e32 v171, s10
	v_sub_f32_e32 v5, v1, v4
	v_cmp_le_f32_e64 s[14:15], s71, v5
	s_lshl_b64 s[12:13], 1, s20
	s_add_u32 s12, s12, -1
	s_addc_u32 s13, s13, -1
	s_and_b64 s[12:13], s[12:13], s[14:15]
	s_ff1_i32_b64 s10, s[12:13]
	s_cmp_lg_u64 s[12:13], 0
	s_cselect_b32 s12, s10, s20
	v_and_b32_e32 v0, 63, v137

.Lgm3_tail:
	s_andn2_b64 vcc, exec, s[10:11]
	s_cbranch_vccnz .Lproj_rs_l0
	v_lshrrev_b32_e32 v254, 1, v198
	v_and_b32_e32 v254, 64, v254
	v_or_b32_e32 v254, s4, v254
	v_and_b32_e32 v220, 15, v198
	v_or_b32_e32 v254, v254, v220
	v_lshlrev_b32_e32 v254, 6, v254
	global_load_dwordx4 v[220:223], v254, s[94:95]
	global_load_dwordx4 v[224:227], v254, s[94:95] offset:16
	global_load_dwordx4 v[228:231], v254, s[94:95] offset:32
	global_load_dwordx4 v[232:235], v254, s[94:95] offset:48
	global_load_dwordx4 v[236:239], v254, s[94:95] offset:1024
	global_load_dwordx4 v[240:243], v254, s[94:95] offset:1040
	global_load_dwordx4 v[244:247], v254, s[94:95] offset:1056
	global_load_dwordx4 v[248:251], v254, s[94:95] offset:1072
.Lproj_rs_l0:
	ds_read_b128 v[156:159], v160 offset:8192
	ds_read_b128 v[162:165], v160 offset:9216
	ds_read_b128 v[166:169], v155
	ds_read_b128 v[170:173], v155 offset:1024
	ds_read_b128 v[174:177], v160 offset:10240
	s_waitcnt lgkmcnt(2)
	v_mfma_f32_16x16x32_bf16 v[178:181], v[162:165], v[166:169], v[120:123]
	s_nop 2
	ds_read_b128 v[120:123], v160 offset:11264
	ds_read_b128 v[182:185], v155 offset:2048
	ds_read_b128 v[186:189], v155 offset:3072
	s_waitcnt lgkmcnt(1)
	v_mfma_f32_16x16x32_bf16 v[190:193], v[156:159], v[182:185], v[108:111]
	s_nop 2
	ds_read_b128 v[108:111], v160 offset:12288
	v_mfma_f32_16x16x32_bf16 v[100:103], v[120:123], v[166:169], v[100:103]
	v_mfma_f32_16x16x32_bf16 v[52:55], v[120:123], v[170:173], v[52:55]
	v_mfma_f32_16x16x32_bf16 v[194:197], v[162:165], v[182:185], v[112:115]
	v_mfma_f32_16x16x32_bf16 v[208:211], v[174:177], v[182:185], v[116:119]
	s_nop 1
	ds_read_b128 v[112:115], v160 offset:13312
	v_mfma_f32_16x16x32_bf16 v[212:215], v[120:123], v[182:185], v[124:127]
	ds_read_b128 v[116:119], v160 offset:14336
	s_waitcnt lgkmcnt(3)
	v_mfma_f32_16x16x32_bf16 v[144:147], v[120:123], v[186:189], v[144:147]
	ds_read_b128 v[120:123], v160 offset:15360
	s_waitcnt vmcnt(4)
	s_waitcnt vmcnt(3)
	s_waitcnt vmcnt(2)
	s_waitcnt vmcnt(1)
	s_waitcnt vmcnt(0)
	s_waitcnt lgkmcnt(0)
	s_barrier
	ds_read_b128 v[0:3], v160 offset:32768
	v_mfma_f32_16x16x32_bf16 v[128:131], v[156:159], v[166:169], v[128:131]
	ds_read_b128 v[4:7], v160 offset:33792
	ds_read_b128 v[8:11], v155 offset:24576
	ds_read_b128 v[16:19], v155 offset:25600
	ds_read_b128 v[20:23], v160 offset:34816
	v_mfma_f32_16x16x32_bf16 v[68:71], v[156:159], v[170:173], v[68:71]
	v_mfma_f32_16x16x32_bf16 v[64:67], v[162:165], v[170:173], v[64:67]
	v_mfma_f32_16x16x32_bf16 v[56:59], v[174:177], v[170:173], v[56:59]
	v_mfma_f32_16x16x32_bf16 v[40:43], v[120:123], v[166:169], v[40:43]
	v_mfma_f32_16x16x32_bf16 v[36:39], v[108:111], v[170:173], v[36:39]
	v_mfma_f32_16x16x32_bf16 v[32:35], v[112:115], v[170:173], v[32:35]
	v_mfma_f32_16x16x32_bf16 v[28:31], v[116:119], v[170:173], v[28:31]
	v_mfma_f32_16x16x32_bf16 v[24:27], v[120:123], v[170:173], v[24:27]
	v_mfma_f32_16x16x32_bf16 v[170:173], v[120:123], v[182:185], v[76:79]
	v_mfma_f32_16x16x32_bf16 v[12:15], v[120:123], v[186:189], v[148:151]
	s_waitcnt lgkmcnt(2)
	v_mfma_f32_16x16x32_bf16 v[120:123], v[0:3], v[8:11], v[128:131]
	s_nop 2
	ds_read_b128 v[128:131], v160 offset:35840
	v_mfma_f32_16x16x32_bf16 v[124:127], v[4:7], v[8:11], v[178:181]
	ds_read_b128 v[148:151], v155 offset:26624
	s_nop 1
	ds_read_b128 v[178:181], v155 offset:27648
	v_mfma_f32_16x16x32_bf16 v[104:107], v[174:177], v[166:169], v[104:107]
	v_mfma_f32_16x16x32_bf16 v[132:135], v[156:159], v[186:189], v[132:135]
	v_mfma_f32_16x16x32_bf16 v[136:139], v[162:165], v[186:189], v[136:139]
	v_mfma_f32_16x16x32_bf16 v[140:143], v[174:177], v[186:189], v[140:143]
	v_mfma_f32_16x16x32_bf16 v[60:63], v[108:111], v[166:169], v[60:63]
	v_mfma_f32_16x16x32_bf16 v[48:51], v[112:115], v[166:169], v[48:51]
	v_mfma_f32_16x16x32_bf16 v[44:47], v[116:119], v[166:169], v[44:47]
	v_mfma_f32_16x16x32_bf16 v[156:159], v[108:111], v[182:185], v[80:83]
	v_mfma_f32_16x16x32_bf16 v[162:165], v[112:115], v[182:185], v[88:91]
	v_mfma_f32_16x16x32_bf16 v[166:169], v[116:119], v[182:185], v[92:95]
	v_mfma_f32_16x16x32_bf16 v[174:177], v[108:111], v[186:189], v[96:99]
	v_mfma_f32_16x16x32_bf16 v[182:185], v[112:115], v[186:189], v[84:87]
	v_mfma_f32_16x16x32_bf16 v[216:219], v[116:119], v[186:189], v[72:75]
	s_waitcnt lgkmcnt(3)
	v_mfma_f32_16x16x32_bf16 v[116:119], v[20:23], v[8:11], v[104:107]
	s_waitcnt lgkmcnt(2)
	v_mfma_f32_16x16x32_bf16 v[112:115], v[128:131], v[8:11], v[100:103]
	v_mfma_f32_16x16x32_bf16 v[108:111], v[0:3], v[16:19], v[68:71]
	v_mfma_f32_16x16x32_bf16 v[104:107], v[4:7], v[16:19], v[64:67]
	v_mfma_f32_16x16x32_bf16 v[96:99], v[128:131], v[16:19], v[52:55]
	s_waitcnt lgkmcnt(1)
	v_mfma_f32_16x16x32_bf16 v[92:95], v[0:3], v[148:151], v[190:193]
	v_mfma_f32_16x16x32_bf16 v[88:91], v[4:7], v[148:151], v[194:197]
	v_mfma_f32_16x16x32_bf16 v[80:83], v[128:131], v[148:151], v[212:215]
	s_waitcnt lgkmcnt(0)
	v_mfma_f32_16x16x32_bf16 v[76:79], v[0:3], v[178:181], v[132:135]
	ds_read_b128 v[0:3], v160 offset:36864
	v_mfma_f32_16x16x32_bf16 v[72:75], v[4:7], v[178:181], v[136:139]
	ds_read_b128 v[4:7], v160 offset:37888
	v_mfma_f32_16x16x32_bf16 v[68:71], v[128:131], v[178:181], v[144:147]
	ds_read_b128 v[130:133], v160 offset:38912
	ds_read_b128 v[134:137], v160 offset:39936
	s_waitcnt lgkmcnt(0)
	v_mfma_f32_16x16x32_bf16 v[100:103], v[20:23], v[16:19], v[56:59]
	s_barrier
	v_mov_b32_e32 v190, 1.0
	v_mov_b32_e32 v191, 1.0
	v_mov_b32_e32 v192, 1.0
	v_mov_b32_e32 v193, 1.0
	s_andn2_b64 vcc, exec, s[10:11]
	s_cbranch_vccnz .Lproj_rs_done
	s_waitcnt vmcnt(4)
	v_add_f32_e32 v255, v220, v221
	v_add_f32_e32 v187, v222, v223
	v_add_f32_e32 v255, v255, v187
	v_add_f32_e32 v186, v224, v225
	v_add_f32_e32 v187, v226, v227
	v_add_f32_e32 v186, v186, v187
	v_add_f32_e32 v255, v255, v186
	v_add_f32_e32 v186, v228, v229
	v_add_f32_e32 v187, v230, v231
	v_add_f32_e32 v186, v186, v187
	v_add_f32_e32 v255, v255, v186
	v_add_f32_e32 v186, v232, v233
	v_add_f32_e32 v187, v234, v235
	v_add_f32_e32 v186, v186, v187
	v_add_f32_e32 v255, v255, v186
	v_fmamk_f32 v255, v255, 0x3a800000, v199
	v_cmp_gt_f32_e32 vcc, s73, v255
	v_mul_f32_e32 v186, 0x4b800000, v255
	s_nop 0
	v_cndmask_b32_e32 v255, v255, v186, vcc
	v_rsq_f32_e32 v255, v255
	s_nop 0
	v_mul_f32_e32 v186, 0x45800000, v255
	v_cndmask_b32_e32 v190, v255, v186, vcc
	global_load_dwordx4 v[220:223], v254, s[94:95] offset:2048
	global_load_dwordx4 v[224:227], v254, s[94:95] offset:2064
	global_load_dwordx4 v[228:231], v254, s[94:95] offset:2080
	global_load_dwordx4 v[232:235], v254, s[94:95] offset:2096
	s_waitcnt vmcnt(4)
	v_add_f32_e32 v255, v236, v237
	v_add_f32_e32 v187, v238, v239
	v_add_f32_e32 v255, v255, v187
	v_add_f32_e32 v186, v240, v241
	v_add_f32_e32 v187, v242, v243
	v_add_f32_e32 v186, v186, v187
	v_add_f32_e32 v255, v255, v186
	v_add_f32_e32 v186, v244, v245
	v_add_f32_e32 v187, v246, v247
	v_add_f32_e32 v186, v186, v187
	v_add_f32_e32 v255, v255, v186
	v_add_f32_e32 v186, v248, v249
	v_add_f32_e32 v187, v250, v251
	v_add_f32_e32 v186, v186, v187
	v_add_f32_e32 v255, v255, v186
	v_fmamk_f32 v255, v255, 0x3a800000, v199
	v_cmp_gt_f32_e32 vcc, s73, v255
	v_mul_f32_e32 v186, 0x4b800000, v255
	s_nop 0
	v_cndmask_b32_e32 v255, v255, v186, vcc
	v_rsq_f32_e32 v255, v255
	s_nop 0
	v_mul_f32_e32 v186, 0x45800000, v255
	v_cndmask_b32_e32 v191, v255, v186, vcc
	global_load_dwordx4 v[236:239], v254, s[94:95] offset:3072
	global_load_dwordx4 v[240:243], v254, s[94:95] offset:3088
	global_load_dwordx4 v[244:247], v254, s[94:95] offset:3104
	global_load_dwordx4 v[248:251], v254, s[94:95] offset:3120
	s_waitcnt vmcnt(4)
	v_add_f32_e32 v255, v220, v221
	v_add_f32_e32 v187, v222, v223
	v_add_f32_e32 v255, v255, v187
	v_add_f32_e32 v186, v224, v225
	v_add_f32_e32 v187, v226, v227
	v_add_f32_e32 v186, v186, v187
	v_add_f32_e32 v255, v255, v186
	v_add_f32_e32 v186, v228, v229
	v_add_f32_e32 v187, v230, v231
	v_add_f32_e32 v186, v186, v187
	v_add_f32_e32 v255, v255, v186
	v_add_f32_e32 v186, v232, v233
	v_add_f32_e32 v187, v234, v235
	v_add_f32_e32 v186, v186, v187
	v_add_f32_e32 v255, v255, v186
	v_fmamk_f32 v255, v255, 0x3a800000, v199
	v_cmp_gt_f32_e32 vcc, s73, v255
	v_mul_f32_e32 v186, 0x4b800000, v255
	s_nop 0
	v_cndmask_b32_e32 v255, v255, v186, vcc
	v_rsq_f32_e32 v255, v255
	s_nop 0
	v_mul_f32_e32 v186, 0x45800000, v255
	v_cndmask_b32_e32 v192, v255, v186, vcc
	s_waitcnt vmcnt(0)
	v_add_f32_e32 v255, v236, v237
	v_add_f32_e32 v187, v238, v239
	v_add_f32_e32 v255, v255, v187
	v_add_f32_e32 v186, v240, v241
	v_add_f32_e32 v187, v242, v243
	v_add_f32_e32 v186, v186, v187
	v_add_f32_e32 v255, v255, v186
	v_add_f32_e32 v186, v244, v245
	v_add_f32_e32 v187, v246, v247
	v_add_f32_e32 v186, v186, v187
	v_add_f32_e32 v255, v255, v186
	v_add_f32_e32 v186, v248, v249
	v_add_f32_e32 v187, v250, v251
	v_add_f32_e32 v186, v186, v187
	v_add_f32_e32 v255, v255, v186
	v_fmamk_f32 v255, v255, 0x3a800000, v199
	v_cmp_gt_f32_e32 vcc, s73, v255
	v_mul_f32_e32 v186, 0x4b800000, v255
	s_nop 0
	v_cndmask_b32_e32 v255, v255, v186, vcc
	v_rsq_f32_e32 v255, v255
	s_nop 0
	v_mul_f32_e32 v186, 0x45800000, v255
	v_cndmask_b32_e32 v193, v255, v186, vcc
.Lproj_rs_done:
	v_mov_b32 v128, v198
	v_mfma_f32_16x16x32_bf16 v[52:55], v[0:3], v[8:11], v[60:63]
	v_and_b32_e32 v129, 63, v128
	v_mfma_f32_16x16x32_bf16 v[56:59], v[4:7], v[8:11], v[48:51]
	v_mfma_f32_16x16x32_bf16 v[60:63], v[130:133], v[8:11], v[44:47]
	v_mfma_f32_16x16x32_bf16 v[48:51], v[134:137], v[8:11], v[40:43]
	v_lshrrev_b32_e32 v8, 1, v128
	v_mfma_f32_16x16x32_bf16 v[84:87], v[20:23], v[148:151], v[208:211]
	v_mfma_f32_16x16x32_bf16 v[64:67], v[20:23], v[178:181], v[140:143]
	v_mfma_f32_16x16x32_bf16 v[44:47], v[0:3], v[16:19], v[36:39]
	v_mfma_f32_16x16x32_bf16 v[40:43], v[4:7], v[16:19], v[32:35]
	v_mfma_f32_16x16x32_bf16 v[36:39], v[130:133], v[16:19], v[28:31]
	v_mfma_f32_16x16x32_bf16 v[32:35], v[134:137], v[16:19], v[24:27]
	v_mfma_f32_16x16x32_bf16 v[28:31], v[0:3], v[148:151], v[156:159]
	v_mfma_f32_16x16x32_bf16 v[20:23], v[4:7], v[148:151], v[162:165]
	v_mfma_f32_16x16x32_bf16 v[16:19], v[130:133], v[148:151], v[166:169]
	v_mfma_f32_16x16x32_bf16 v[24:27], v[134:137], v[148:151], v[170:173]
	v_and_or_b32 v148, v8, 64, s4
	v_lshlrev_b32_e32 v8, 1, v128
	v_and_b32_e32 v8, 0x80, v8
	v_mfma_f32_16x16x32_bf16 v[0:3], v[0:3], v[178:181], v[174:177]
	v_or_b32_e32 v151, s17, v8
	v_lshrrev_b32_e32 v150, 6, v151
	s_movk_i32 s4, 0xc01
	v_mfma_f32_16x16x32_bf16 v[4:7], v[4:7], v[178:181], v[182:185]
	v_and_b32_e32 v149, 15, v128
	v_cmp_gt_u32_e32 vcc, s4, v151
	v_and_b32_e32 v156, 60, v150
	v_mfma_f32_16x16x32_bf16 v[8:11], v[130:133], v[178:181], v[216:219]
	v_mfma_f32_16x16x32_bf16 v[12:15], v[134:137], v[178:181], v[12:15]
	s_and_saveexec_b64 s[20:21], vcc
	s_cbranch_execz .LBB0_591
	v_cmp_ne_u32_e32 vcc, 8, v156
	s_and_saveexec_b64 s[6:7], vcc
	s_xor_b64 s[6:7], exec, s[6:7]
	s_cbranch_execz .LBB0_485
	s_and_b32 s4, s17, 0xe00
	s_cmpk_eq_i32 s4, 0x400
	s_cbranch_scc1 .LBB0_616
	v_cmp_lt_i32_e32 vcc, 31, v150
	s_mov_b64 s[34:35], 0
	s_mov_b64 s[28:29], 0
	s_and_saveexec_b64 s[4:5], vcc
	s_xor_b64 s[4:5], exec, s[4:5]
	s_cbranch_execz .LBB0_462
	v_cmp_lt_i32_e32 vcc, 33, v150
	s_mov_b64 s[22:23], 0
	s_mov_b64 s[24:25], 0
	s_and_saveexec_b64 s[26:27], vcc
	s_xor_b64 s[26:27], exec, s[26:27]
	s_cbranch_execz .LBB0_459
	v_cmp_eq_u32_e32 vcc, 34, v150
	s_mov_b64 s[24:25], -1
	s_and_saveexec_b64 s[28:29], vcc
	s_xor_b64 s[24:25], exec, -1
	s_or_b64 exec, exec, s[28:29]
	s_and_b64 s[24:25], s[24:25], exec

.LBB0_487:
	s_or_b64 exec, exec, s[6:7]
	v_cndmask_b32_e64 v132, 0, 1, s[10:11]
	v_or_b32_e32 v162, v148, v149
	v_cmp_ne_u32_e64 s[6:7], 1, v132
	s_andn2_b64 vcc, exec, s[10:11]
	v_mov_b32_e32 v142, 1.0
	s_cbranch_vccnz .LBB0_489
	v_mov_b32_e32 v142, v190

.LBB0_513:
	s_or_b64 exec, exec, s[30:31]
	v_or_b32_e32 v113, 16, v162
	s_and_b64 vcc, exec, s[6:7]
	v_mov_b32_e32 v114, 1.0
	s_cbranch_vccnz .LBB0_515
	v_mov_b32_e32 v114, v191

.LBB0_539:
	s_or_b64 exec, exec, s[30:31]
	v_or_b32_e32 v110, 32, v162
	s_and_b64 vcc, exec, s[6:7]
	v_mov_b32_e32 v96, 1.0
	s_cbranch_vccnz .LBB0_541
	v_mov_b32_e32 v96, v192

.LBB0_565:
	s_or_b64 exec, exec, s[30:31]
	v_or_b32_e32 v94, 48, v162
	s_and_b64 vcc, exec, s[6:7]
	v_mov_b32_e32 v80, 1.0
	s_cbranch_vccnz .LBB0_567
	v_mov_b32_e32 v80, v193

.LBB0_668:
	s_or_b64 exec, exec, s[4:5]
	v_cndmask_b32_e64 v65, 0, 1, s[10:11]
	v_or_b32_e32 v83, v148, v149
	v_cmp_ne_u32_e64 s[6:7], 1, v65
	s_andn2_b64 vcc, exec, s[10:11]
	v_mov_b32_e32 v82, 1.0
	s_cbranch_vccnz .LBB0_670
	v_mov_b32_e32 v82, v190

.LBB0_678:
	s_or_b64 exec, exec, s[28:29]
	v_or_b32_e32 v49, 16, v83
	s_and_b64 vcc, exec, s[6:7]
	v_mov_b32_e32 v74, 1.0
	s_cbranch_vccnz .LBB0_680
	v_mov_b32_e32 v74, v191

.LBB0_684:
	s_or_b64 exec, exec, s[28:29]
	v_or_b32_e32 v46, 32, v83
	s_and_b64 vcc, exec, s[6:7]
	v_mov_b32_e32 v40, 1.0
	s_cbranch_vccnz .LBB0_686
	v_mov_b32_e32 v40, v192

.LBB0_690:
	s_or_b64 exec, exec, s[28:29]
	v_or_b32_e32 v30, 48, v83
	s_and_b64 vcc, exec, s[6:7]
	v_mov_b32_e32 v28, 1.0
	s_cbranch_vccnz .LBB0_692
	v_mov_b32_e32 v28, v193
